# mixer_post rwkv loop: per-channel constant vectors loaded once before the loop, single wait per iteration; on top of recurrence inner-loop rewrites
# baseline (speedup 1.0000x reference)
; __device__ __forceinline__ unsigned cvt_pk_bf16(float lo, float hi) { const bf16x2n v = __builtin_convertvector((f32x2){lo, hi}, bf16x2n); return __builtin_bit_cast(unsigned, v); }
; __device__ __forceinline__ float bflo(unsigned u) { return __uint_as_float(u << 16); }
; __device__ __forceinline__ float bfhi(unsigned u) { return __uint_as_float(u & 0xffff0000u); }
; __device__ __forceinline__ void mixer_post(const Params& P, int wg, int nwg, bool dry) {
;     ...
;     for (int it0 = gw * 4; it0 < T * 16; it0 += ngw * 4) {
;         const int it = it0 + sub, t = it >> 4, hh = it & 15, c = hh * 64 + l16 * 4;
;         const size_t pr = (size_t)t * PLD;
;         const u32x2 yu = *(const u32x2*)(proj + pr + PC_K + c), rcu = *(const u32x2*)(proj + pr + PC_R + c), vcu = *(const u32x2*)(proj + pr + PC_V + c);
;         u32x2 rpu = {0u, 0u}, vpu = {0u, 0u};
;         if (t > 0) { rpu = *(const u32x2*)(proj + pr - PLD + PC_R + c); vpu = *(const u32x2*)(proj + pr - PLD + PC_V + c); }
;         const u32x2 kpu = *(const u32x2*)(i_kp + (size_t)t * 1024 + c), ggu = *(const u32x2*)(i_g + (size_t)t * 1024 + c);
;         const f32x4 mur = *(const f32x4*)(mu + c), muv = *(const f32x4*)(mu + 2048 + c), rk = *(const f32x4*)(r_k + c), lw = *(const f32x4*)(ln_w + c), lb = *(const f32x4*)(ln_b + c);
;         const f32x4 y = {bflo(yu.x), bfhi(yu.x), bflo(yu.y), bfhi(yu.y)}, rc = {bflo(rcu.x), bfhi(rcu.x), bflo(rcu.y), bfhi(rcu.y)}, vc = {bflo(vcu.x), bfhi(vcu.x), bflo(vcu.y), bfhi(vcu.y)};
;         const f32x4 rp = {bflo(rpu.x), bfhi(rpu.x), bflo(rpu.y), bfhi(rpu.y)}, vp = {bflo(vpu.x), bfhi(vpu.x), bflo(vpu.y), bfhi(vpu.y)};
;         const f32x4 kp = {bflo(kpu.x), bfhi(kpu.x), bflo(kpu.y), bfhi(kpu.y)}, gg = {bflo(ggu.x), bfhi(ggu.x), bflo(ggu.y), bfhi(ggu.y)};
;         const float mean = red16(y.x + y.y + y.z + y.w) * (1.f / 64.f);
;         const f32x4 d = y - mean;
;         const float var = red16(d.x * d.x + d.y * d.y + d.z * d.z + d.w * d.w) * (1.f / 64.f);
;         const f32x4 r = rc + (rp - rc) * mur, v = vc + (vp - vc) * muv;
;         const f32x4 rkk = r * kp * rk;
;         const float bs = red16(rkk.x + rkk.y + rkk.z + rkk.w);
;         const f32x4 o = (d * rsqrtf(var + 64e-5f) * lw + lb + v * bs) * gg;
;         if (!dry || o.x != o.x) { u32x2 w; w.x = cvt_pk_bf16(o.x, o.y); w.y = cvt_pk_bf16(o.z, o.w); *(u32x2*)(proj + pr + PC_K + c) = w; }
.LBB0_741:
	s_or_b64 exec, exec, s[8:9]
	s_load_dwordx2 s[8:9], s[0:1], 0x128
	s_waitcnt lgkmcnt(0)
	v_lshrrev_b32_e32 v2, 4, v158
	v_and_b32_e32 v2, 60, v2
	s_mov_b32 s10, 0x40000
	v_bfe_u32 v156, v158, 4, 2
	s_add_u32 s12, s8, 0xdc00000
	s_addc_u32 s13, s9, 0
	s_lshl_b32 s40, s2, 5
	s_waitcnt vmcnt(4)
	v_add_u32_e32 v20, s40, v2
	v_cmp_gt_i32_e32 vcc, s10, v20
	s_barrier
	s_and_saveexec_b64 s[14:15], vcc
	s_cbranch_execz .LBB0_746
	s_add_u32 s16, s8, 0x1cc00000
	s_addc_u32 s17, s9, 0
	s_load_dwordx2 s[54:55], s[0:1], 0x40
	s_add_u32 s18, s8, 0x7400000
	s_addc_u32 s19, s9, 0
	s_load_dwordx4 s[8:11], s[0:1], 0x80
	s_load_dwordx2 s[56:57], s[0:1], 0x90
	v_lshlrev_b32_e32 v21, 2, v130
	s_waitcnt lgkmcnt(0)
	s_add_u32 s58, s54, 0x2000
	s_addc_u32 s59, s55, 0
	s_lshl_b32 s41, s28, 5
	s_mov_b64 s[60:61], 0
	s_movk_i32 s43, 0x3400
	v_mov_b64_e32 v[2:3], s[12:13]
	v_mov_b32_e32 v5, 0
	s_waitcnt vmcnt(3)
	v_mov_b32_e32 v22, 0x3a27c5ac
	s_mov_b32 s64, 0x800000
	s_mov_b32 s65, 0x3ffff
	v_mov_b32_e32 v23, v20
	v_and_or_b32 v4, v23, 12, v156
	v_lshl_or_b32 v24, v4, 6, v21
	v_lshlrev_b32_e32 v40, 2, v24
	global_load_dwordx4 v[200:203], v40, s[54:55]
	global_load_dwordx4 v[204:207], v40, s[10:11]
	global_load_dwordx4 v[208:211], v40, s[56:57]
	global_load_dwordx4 v[212:215], v40, s[8:9]
	global_load_dwordx4 v[216:219], v40, s[58:59]
	s_waitcnt vmcnt(0)
	s_branch .LBB0_744
.LBB0_743:
	s_or_b64 exec, exec, s[62:63]
	v_ashrrev_i32_e32 v19, 31, v18
	v_lshlrev_b64 v[18:19], 11, v[18:19]
	v_lshl_add_u64 v[36:37], s[16:17], 0, v[18:19]
	v_lshlrev_b32_e32 v40, 2, v24
	v_lshl_add_u64 v[36:37], v[36:37], 0, v[4:5]
	global_load_dwordx2 v[44:45], v[36:37], off
	v_lshl_add_u64 v[18:19], s[18:19], 0, v[18:19]
	v_lshl_add_u64 v[18:19], v[18:19], 0, v[4:5]
	global_load_dwordx2 v[18:19], v[18:19], off
	s_nop 0
	s_waitcnt vmcnt(0)
	v_lshlrev_b32_e32 v46, 16, v10
	v_and_b32_e32 v47, 0xffff0000, v10
	v_lshlrev_b32_e32 v10, 16, v11
	s_waitcnt vmcnt(7)
	v_lshlrev_b32_e32 v48, 16, v12
	v_lshlrev_b32_e32 v4, 16, v16
	v_add_f32_e32 v54, v46, v47
	v_and_b32_e32 v11, 0xffff0000, v11
	v_lshlrev_b32_e32 v58, 16, v14
	v_and_b32_e32 v53, 0xffff0000, v14
	v_sub_f32_e32 v14, v4, v48
	v_add_f32_e32 v4, v54, v10
	v_add_f32_e32 v4, v4, v11
	v_and_b32_e32 v49, 0xffff0000, v12
	v_lshlrev_b32_e32 v12, 16, v13
	v_add_f32_dpp v4, v4, v4 quad_perm:[1,0,3,2] row_mask:0xf bank_mask:0xf bound_ctrl:1
	v_and_b32_e32 v16, 0xffff0000, v16
	v_lshlrev_b32_e32 v52, 16, v17
	v_add_f32_dpp v4, v4, v4 quad_perm:[2,3,0,1] row_mask:0xf bank_mask:0xf bound_ctrl:1
	v_lshlrev_b32_e32 v59, 16, v15
	v_and_b32_e32 v60, 0xffff0000, v15
	v_add_f32_dpp v4, v4, v4 row_half_mirror row_mask:0xf bank_mask:0xf bound_ctrl:1
	v_sub_f32_e32 v15, v16, v49
	v_sub_f32_e32 v16, v52, v12
	v_add_f32_dpp v4, v4, v4 row_mirror row_mask:0xf bank_mask:0xf bound_ctrl:1
	v_fmac_f32_e32 v47, 0xbc800000, v4
	v_fmac_f32_e32 v46, 0xbc800000, v4
	v_fmac_f32_e32 v11, 0xbc800000, v4
	v_fmac_f32_e32 v10, 0xbc800000, v4
	v_pk_mul_f32 v[56:57], v[46:47], v[46:47]
	v_pk_mul_f32 v[54:55], v[10:11], v[10:11]
	v_add_f32_e32 v4, v56, v57
	v_add_f32_e32 v4, v54, v4
	v_add_f32_e32 v4, v55, v4
	v_and_b32_e32 v13, 0xffff0000, v13
	v_and_b32_e32 v17, 0xffff0000, v17
	v_add_f32_dpp v4, v4, v4 quad_perm:[1,0,3,2] row_mask:0xf bank_mask:0xf bound_ctrl:1
	v_sub_f32_e32 v17, v17, v13
	v_lshlrev_b32_e32 v50, 16, v8
	v_add_f32_dpp v4, v4, v4 quad_perm:[2,3,0,1] row_mask:0xf bank_mask:0xf bound_ctrl:1
	v_and_b32_e32 v51, 0xffff0000, v8
	v_lshlrev_b32_e32 v8, 16, v9
	v_add_f32_dpp v4, v4, v4 row_half_mirror row_mask:0xf bank_mask:0xf bound_ctrl:1
	v_and_b32_e32 v9, 0xffff0000, v9
	v_sub_f32_e32 v53, v53, v51
	v_add_f32_dpp v4, v4, v4 row_mirror row_mask:0xf bank_mask:0xf bound_ctrl:1
	v_fmamk_f32 v4, v4, 0x3c800000, v22
	v_mul_f32_e32 v52, 0x4b800000, v4
	v_cmp_gt_f32_e32 vcc, s64, v4
	v_sub_f32_e32 v55, v60, v9
	v_sub_f32_e32 v54, v59, v8
	v_cndmask_b32_e32 v4, v4, v52, vcc
	v_rsq_f32_e32 v4, v4
	v_sub_f32_e32 v52, v58, v50
	v_add_u32_e32 v23, s41, v23
	v_mul_f32_e32 v56, 0x45800000, v4
	v_cndmask_b32_e32 v4, v4, v56, vcc
	v_pk_mul_f32 v[46:47], v[46:47], v[4:5] op_sel_hi:[1,0]
	v_pk_mul_f32 v[10:11], v[10:11], v[4:5] op_sel_hi:[1,0]
	v_cmp_lt_i32_e32 vcc, s65, v23
	s_or_b64 s[60:61], vcc, s[60:61]
	s_waitcnt vmcnt(6)
	v_pk_fma_f32 v[14:15], v[200:201], v[14:15], v[48:49]
	v_pk_fma_f32 v[12:13], v[202:203], v[16:17], v[12:13]
	s_waitcnt vmcnt(4)
	v_pk_fma_f32 v[10:11], v[206:207], v[10:11], v[210:211]
	s_waitcnt vmcnt(3)
	v_lshlrev_b32_e32 v24, 16, v44
	v_and_b32_e32 v25, 0xffff0000, v44
	v_lshlrev_b32_e32 v26, 16, v45
	v_and_b32_e32 v27, 0xffff0000, v45
	v_pk_mul_f32 v[14:15], v[14:15], v[24:25]
	v_pk_mul_f32 v[12:13], v[12:13], v[26:27]
	s_waitcnt vmcnt(1)
	v_pk_mul_f32 v[14:15], v[212:213], v[14:15]
	v_pk_mul_f32 v[12:13], v[214:215], v[12:13]
	v_add_f32_e32 v4, v14, v15
	v_add_f32_e32 v4, v12, v4
	v_add_f32_e32 v4, v13, v4
	v_pk_fma_f32 v[16:17], v[204:205], v[46:47], v[208:209]
	s_waitcnt vmcnt(0)
	v_pk_fma_f32 v[8:9], v[218:219], v[54:55], v[8:9]
	v_add_f32_dpp v4, v4, v4 quad_perm:[1,0,3,2] row_mask:0xf bank_mask:0xf bound_ctrl:1
	v_pk_fma_f32 v[12:13], v[216:217], v[52:53], v[50:51]
	v_lshlrev_b32_e32 v28, 16, v18
	v_add_f32_dpp v4, v4, v4 quad_perm:[2,3,0,1] row_mask:0xf bank_mask:0xf bound_ctrl:1
	v_and_b32_e32 v29, 0xffff0000, v18
	v_lshlrev_b32_e32 v18, 16, v19
	v_add_f32_dpp v4, v4, v4 row_half_mirror row_mask:0xf bank_mask:0xf bound_ctrl:1
	v_and_b32_e32 v19, 0xffff0000, v19
	s_nop 0
	v_add_f32_dpp v4, v4, v4 row_mirror row_mask:0xf bank_mask:0xf bound_ctrl:1
	v_pk_fma_f32 v[12:13], v[12:13], v[4:5], v[16:17] op_sel_hi:[1,0,1]
	v_pk_fma_f32 v[8:9], v[8:9], v[4:5], v[10:11] op_sel_hi:[1,0,1]
	v_pk_mul_f32 v[10:11], v[12:13], v[28:29]
	v_pk_mul_f32 v[8:9], v[8:9], v[18:19]
	v_cvt_pk_bf16_f32 v10, v10, v11
	v_cvt_pk_bf16_f32 v11, v8, v9
	global_store_dwordx2 v[6:7], v[10:11], off offset:2048
	s_andn2_b64 exec, exec, s[60:61]
	s_cbranch_execz .LBB0_746
